# attention loops: ballot trim (7.12), redundant canonicalizing v_max removed, K/V tile load addresses via scalar bases; plus DIFFC DPP row reduction
# speedup vs baseline: 1.0074x; 1.0074x over previous
; #define SBAR() __builtin_amdgcn_sched_barrier(0)
; #define SWRITE(b) SWRITE2(b, b)
; #define SWAIT() asm volatile("s_waitcnt vmcnt(0)" ::: "memory")
; template <int DK, int DV, int LDQ, int LDK, int LDV, int LDO, typename TOut, bool PIPE, bool QL, bool VS>
; __device__ __forceinline__ void attn_body16(const bf16_t* Qb, const bf16_t* Kh, const bf16_t* Vh, TOut* Ob, int seq, char* lds) {
;     ...
;     for (int ks = 0; ks < DK / 32; ++ks) { const bf16x8 qv = *reinterpret_cast<const bf16x8*>(Qb + (long)(wid * QBLK + qt * 16 + c) * LDQ + ks * 32 + g * 8);
;       if constexpr (QL) { *reinterpret_cast<bf16x8*>(Q_lds + (qt * 16 + c) * (DK * 2) + (((ks * 32 + g * 8) * 2) ^ ((c & 7) << 4))) = qv; if (qt == 0 && ks == 0) qr[0][0] = qv; } else qr[qt][ks] = qv; }
;     ...
;   const int vb0 = (int)(uintptr_t)V_lds + (4 * g + (c >> 2)) * VRSB + (c & 3) * 8;
;   struct { bf16x8 vs[VP], ks[PIPE ? KP : 1]; } sr_;
;   const int widu = __builtin_amdgcn_readfirstlane(wid);
;     ...
;   bf16x8 pa[2][2]; const int NT = seq / KVBLK;
;   if constexpr (PIPE) {
;     f32x4 sA[4][2], sB[4][2]; float alA[2], alB[2];
;     SLOAD(0); asm volatile("s_waitcnt vmcnt(0)" ::: "memory"); SWRITE(0); __syncthreads();
;     QKT(sA, K_lds); partialSM16(sA, m_reg, alA, C, THR_S);
;     SLOAD(KVBLK);
;     SWAIT(); SWRITE(1); __syncthreads();
;     for (int j = 1; j + 1 < NT; j += 2) {
;       SLOAD((j + 1) * KVBLK); SBAR(); QKT(sB, K_lds + SHM_K); SBAR();
;       finishSM16(sA, alA, lp, pa); SBAR();
;       pv16<NVT, VRSB>(o, vb0, pa); partialSM16(sB, m_reg, alB, C, THR_S);
;       __syncthreads(); SWAIT(); SWRITE(0);
;       RESC(alB); __syncthreads();
;       SLOAD((j + 2) * KVBLK); SBAR(); QKT(sA, K_lds); SBAR();
;       finishSM16(sB, alB, lp, pa); SBAR();
;       pv16<NVT, VRSB>(o, vb0 + (int)SHM_V, pa); partialSM16(sA, m_reg, alA, C, THR_S);
;       __syncthreads(); SWAIT(); SWRITE(1);
;       RESC(alA); __syncthreads();
;     }
;     SBAR(); QKT(sB, K_lds + SHM_K); SBAR();
;     finishSM16(sA, alA, lp, pa); SBAR();
;     pv16<NVT, VRSB>(o, vb0, pa); partialSM16(sB, m_reg, alB, C, THR_S);
;     __syncthreads(); RESC(alB);
;     finishSM16(sB, alB, lp, pa); SBAR();
;     pv16<NVT, VRSB>(o, vb0 + (int)SHM_V, pa);
;   } else {
;     f32x4 s[4][2]; float al[2];
;     VLOAD(0); KDMA(0, 0); asm volatile("s_waitcnt vmcnt(0)" ::: "memory"); VWRITE(0); __syncthreads();
.LBB0_673:
	s_andn2_b64 vcc, exec, s[6:7]
	s_cbranch_vccnz .LBB0_668
	s_ashr_i32 s27, s26, 3
	s_and_b32 s28, s26, 7
	s_mul_i32 s7, s27, 0x1100
	s_mul_hi_i32 s6, s27, 0x1100
	s_add_u32 s12, s7, s4
	s_addc_u32 s13, s6, s5
	s_mul_i32 s4, s13, 0xc00
	s_mul_hi_u32 s5, s12, 0xc00
	s_add_i32 s5, s5, s4
	s_mul_i32 s4, s12, 0xc00
	s_add_u32 s4, s1, s4
	s_addc_u32 s5, s16, s5
	s_mul_i32 s33, s28, 0x180
	s_add_u32 s6, s4, s33
	s_addc_u32 s7, s5, 0
	s_mul_i32 s37, s27, 0xcc0000
	v_mov_b32_e32 v22, v0
	s_mul_hi_i32 s36, s27, 0xcc0000
	s_add_u32 s4, s17, s37
	s_addc_u32 s5, s20, s36
	v_add_u32_e32 v17, 0x200, v22
	v_ashrrev_i32_e32 v2, 31, v22
	v_ashrrev_i32_e32 v6, 31, v17
	s_add_u32 s4, s4, s33
	v_ashrrev_i32_e32 v155, 6, v22
	v_bfe_u32 v170, v22, 4, 2
	v_lshrrev_b32_e32 v2, 28, v2
	v_lshrrev_b32_e32 v6, 28, v6
	s_addc_u32 s5, s5, 0
	s_mul_i32 s39, s27, 0x880000
	v_and_b32_e32 v171, 15, v22
	v_lshlrev_b32_e32 v154, 5, v155
	v_lshlrev_b32_e32 v10, 4, v170
	v_mov_b32_e32 v11, v179
	v_add_u32_e32 v2, v22, v2
	v_add_u32_e32 v6, v17, v6
	s_mul_hi_i32 s38, s27, 0x880000
	s_add_u32 s27, s21, s39
	v_or_b32_e32 v15, v154, v171
	v_lshl_add_u64 v[12:13], s[6:7], 0, v[10:11]
	v_ashrrev_i32_e32 v11, 4, v2
	v_and_b32_e32 v2, 0xffffff0, v2
	v_ashrrev_i32_e32 v23, 4, v6
	v_and_b32_e32 v6, 0xffffff0, v6
	s_addc_u32 s29, s22, s38
	s_lshl_b32 s26, s28, 7
	s_lshl_b32 s46, s28, 8
	v_sub_u32_e32 v2, v22, v2
	v_sub_u32_e32 v6, v17, v6
	v_mad_i64_i32 v[18:19], s[6:7], v15, s47, v[12:13]
	v_or_b32_e32 v15, 16, v15
	s_add_u32 s28, s27, s46
	v_lshlrev_b32_e32 v177, 4, v2
	v_lshlrev_b32_e32 v186, 4, v6
	v_mad_i64_i32 v[12:13], s[6:7], v15, s47, v[12:13]
	s_addc_u32 s29, s29, 0
	v_lshl_add_u32 v14, v11, 11, v177
	v_lshl_add_u32 v16, v23, 11, v186
	v_readfirstlane_b32 s6, v155
	s_add_i32 s50, 0, 0x15000
	global_load_dwordx4 v[2:5], v14, s[28:29]
	global_load_dwordx4 v[6:9], v16, s[28:29]
	s_lshl_b32 s28, s6, 10
	s_add_i32 s27, 0, 0x9000
	s_cmp_lg_u32 s27, -1
	s_cselect_b32 s6, s27, 0
	s_add_i32 s28, s28, s6
	s_mov_b32 s6, 0x2aaaaaab
	global_load_dwordx4 v[102:105], v[18:19], off
	global_load_dwordx4 v[94:97], v[18:19], off offset:64
	global_load_dwordx4 v[86:89], v[18:19], off offset:128
	global_load_dwordx4 v[78:81], v[18:19], off offset:192
	global_load_dwordx4 v[70:73], v[18:19], off offset:256
	global_load_dwordx4 v[66:69], v[18:19], off offset:320
	global_load_dwordx4 v[110:113], v[12:13], off
	global_load_dwordx4 v[106:109], v[12:13], off offset:64
	global_load_dwordx4 v[98:101], v[12:13], off offset:128
	global_load_dwordx4 v[90:93], v[12:13], off offset:192
	global_load_dwordx4 v[82:85], v[12:13], off offset:256
	global_load_dwordx4 v[74:77], v[12:13], off offset:320
	v_mul_hi_i32 v12, v22, s6
	v_lshrrev_b32_e32 v13, 31, v12
	v_ashrrev_i32_e32 v12, 2, v12
	v_add_u32_e32 v12, v12, v13
	v_mul_lo_u32 v13, v12, 24
	v_sub_u32_e32 v13, v22, v13
	v_bitop3_b32 v13, v12, v13, 7 bitop3:0x6c
	v_mul_lo_u32 v12, v12, s47
	v_lshl_add_u32 v12, v13, 4, v12
	v_mul_hi_i32 v13, v17, s6
	v_lshrrev_b32_e32 v15, 31, v13
	v_ashrrev_i32_e32 v13, 2, v13
	v_add_u32_e32 v13, v13, v15
	v_mul_lo_u32 v15, v13, 24
	v_sub_u32_e32 v15, v17, v15
	v_bitop3_b32 v15, v13, v15, 7 bitop3:0x6c
	v_mul_lo_u32 v13, v13, s47
	v_lshl_add_u32 v18, v15, 4, v13
	v_add_u32_e32 v13, 0x400, v22
	v_mul_hi_i32 v15, v13, s6
	v_lshrrev_b32_e32 v17, 31, v15
	v_ashrrev_i32_e32 v15, 2, v15
	v_add_u32_e32 v15, v15, v17
	v_mul_lo_u32 v17, v15, 24
	s_mov_b32 m0, s28
	v_sub_u32_e32 v13, v13, v17
	global_load_lds_dwordx4 v12, s[4:5]
	s_add_i32 m0, s28, 0x2000
	v_bitop3_b32 v13, v15, v13, 7 bitop3:0x6c
	v_mul_lo_u32 v15, v15, s47
	global_load_lds_dwordx4 v18, s[4:5]
	v_lshl_add_u32 v20, v13, 4, v15
	s_add_i32 m0, s28, 0x4000
	s_cmp_lg_u32 0, -1
	global_load_lds_dwordx4 v20, s[4:5]
	s_movk_i32 s4, 0x120
	v_mul_lo_u32 v187, v11, s4
	v_add3_u32 v11, 0, v187, v177
	v_mul_lo_u32 v188, v23, s4
	s_waitcnt vmcnt(0)
	s_cselect_b32 s6, 0, 0
	s_add_i32 s30, s30, 1
	v_and_b32_e32 v13, 0x3fffffc0, v22
	v_lshl_add_u32 v24, v13, 2, s50
	v_mov_b32_e32 v13, v179
	v_mov_b32_e32 v19, v179
	v_mov_b32_e32 v21, v179
	v_lshlrev_b32_e32 v178, 4, v171
	s_movk_i32 s4, 0x70
	v_bitop3_b32 v190, v10, v178, s4 bitop3:0x78
	s_movk_i32 s4, 0xc0
	v_mov_b32_e32 v15, v179
	v_mov_b32_e32 v17, v179
	v_mov_b32_e32 v58, v179
	v_mov_b32_e32 v59, v179
	v_mov_b32_e32 v60, v179
	v_mov_b32_e32 v61, v179
	v_lshl_add_u32 v173, v171, 2, v24
	v_add_u32_e32 v172, v24, v10
	v_mov_b32_e32 v156, 0
	v_mov_b64_e32 v[50:51], v[58:59]
	v_mov_b64_e32 v[42:43], v[58:59]
	v_mov_b64_e32 v[34:35], v[58:59]
	v_mov_b64_e32 v[26:27], v[58:59]
	v_mov_b64_e32 v[64:65], v[60:61]
	v_mov_b64_e32 v[54:55], v[58:59]
	v_mov_b64_e32 v[46:47], v[58:59]
	s_waitcnt vmcnt(0)
	ds_write_b128 v11, v[2:5]
	v_add3_u32 v2, 0, v188, v186
	ds_write_b128 v2, v[6:9]
	v_bfe_u32 v2, v22, 2, 2
	v_lshl_or_b32 v2, v170, 2, v2
	v_lshlrev_b32_e32 v3, 3, v22
	v_mul_u32_u24_e32 v2, 0x120, v2
	v_and_b32_e32 v3, 24, v3
	v_add3_u32 v174, v3, s6, v2
	s_or_b32 s6, s37, s33
	s_add_u32 s6, s6, 0x325d0000
	s_addc_u32 s7, s36, 0
	v_and_b32_e32 v4, 0x70, v178
	v_lshl_add_u64 v[158:159], s[6:7], 0, v[12:13]
	v_lshl_add_u64 v[160:161], s[6:7], 0, v[18:19]
	v_lshl_add_u64 v[162:163], s[6:7], 0, v[20:21]
	s_or_b32 s6, s39, s46
	v_bitop3_b32 v193, v10, v4, s4 bitop3:0x36
	s_movk_i32 s4, 0x100
	s_add_u32 s6, s6, 0x358c0000
	v_bitop3_b32 v194, v10, v4, s4 bitop3:0x36
	s_movk_i32 s4, 0x140
	s_addc_u32 s7, s38, 0
	v_bitop3_b32 v191, v10, v4, 64 bitop3:0x36
	v_bitop3_b32 v192, v10, v4, s14 bitop3:0x36
	v_bitop3_b32 v195, v10, v4, s4 bitop3:0x36
	v_lshl_add_u64 v[164:165], s[6:7], 0, v[14:15]
	v_lshl_add_u64 v[166:167], s[6:7], 0, v[16:17]
	v_mov_b64_e32 v[18:19], v[58:59]
	v_mov_b64_e32 v[10:11], v[58:59]
	v_mov_b64_e32 v[2:3], v[58:59]
	v_mov_b64_e32 v[38:39], v[58:59]
	v_mov_b64_e32 v[30:31], v[58:59]
	v_mov_b64_e32 v[22:23], v[58:59]
	v_mov_b64_e32 v[14:15], v[58:59]
	v_mov_b64_e32 v[6:7], v[58:59]
	s_mov_b32 s29, 0
	v_mul_u32_u24_e32 v189, 0x180, v171
	v_cmp_eq_u32_e64 s[4:5], 0, v170
	v_mov_b32_e32 v175, 0xf149f2ca
	v_mov_b64_e32 v[52:53], v[60:61]
	v_mov_b64_e32 v[44:45], v[60:61]
	v_mov_b64_e32 v[36:37], v[60:61]
	v_mov_b64_e32 v[28:29], v[60:61]
	v_mov_b64_e32 v[20:21], v[60:61]
	v_mov_b64_e32 v[12:13], v[60:61]
	v_mov_b64_e32 v[4:5], v[60:61]
	v_mov_b64_e32 v[62:63], v[58:59]
	v_mov_b64_e32 v[56:57], v[60:61]
	v_mov_b64_e32 v[48:49], v[60:61]
	v_mov_b64_e32 v[40:41], v[60:61]
	v_mov_b64_e32 v[32:33], v[60:61]
	v_mov_b64_e32 v[24:25], v[60:61]
	v_mov_b64_e32 v[16:17], v[60:61]
	v_mov_b64_e32 v[8:9], v[60:61]
	v_mov_b32_e32 v176, 0xf149f2ca
	v_mov_b32_e32 v157, v156
	s_waitcnt lgkmcnt(0)
	s_barrier
	s_mov_b64 s[52:53], s[8:9]
	s_mov_b64 s[54:55], s[8:9]
	s_branch .LBB0_677

; #define SBAR() __builtin_amdgcn_sched_barrier(0)
; #define RESC(a) do { if (__any((a) < 1.f)) { if (hi == 0) al_l[r32] = (a); asm volatile("s_waitcnt lgkmcnt(0)" ::: "memory"); \
;     _Pragma("unroll") for (int d = 0; d < 4; ++d) _Pragma("unroll") for (int r = 0; r < 16; ++r) o[d][r] *= al_l[crow(r, hi)]; } } while (0)
; template <int NVT, int VRSB, int KB, int DH, int VT> __device__ __forceinline__ void pvh_pro(int vb, s16x4 (&f)[DH + 1][2]) { if constexpr (VT < DH && VT < NVT) { pvh_ld<VT, KB, VRSB>(f[VT], vb); pvh_pro<NVT, VRSB, KB, DH, VT + 1>(vb, f); } }
; __device__ __forceinline__ void partialSM16(f32x4 (&s)[4][2], float (&m_reg)[2], float (&alpha)[2], const float C, const float thr_s) {
;     ...
;   for (int qt = 0; qt < 2; ++qt) { const float mnC = -mn[qt] * C;
; #pragma unroll
;     for (int kt = 0; kt < 4; ++kt)
; #pragma unroll
;       for (int r = 0; r < 4; ++r) s[kt][qt][r] = fmaf(s[kt][qt][r], C, mnC); }
; #pragma unroll
;   for (int qt = 0; qt < 2; ++qt)
; #pragma unroll
;     for (int kt = 0; kt < 2; ++kt)
; #pragma unroll
;       for (int r = 0; r < 4; ++r) s[kt][qt][r] = __builtin_amdgcn_exp2f(s[kt][qt][r]);
; template <int DK, int DV, int LDQ, int LDK, int LDV, int LDO, typename TOut, bool PIPE, bool QL, bool VS>
; __device__ __forceinline__ void attn_body16(const bf16_t* Qb, const bf16_t* Kh, const bf16_t* Vh, TOut* Ob, int seq, char* lds) {
;     ...
;       partialSM16(s, m_reg, al, C, THR_S);
;       RESC(al);
;       constexpr int DH = 3; s16x4 pvf[DH + 1][2]; const int vbt = vb0 + vsel * (int)SHM_V;
;       pvh_pro<NVT, VRSB, 0, DH, 0>(vbt, pvf); SBAR();
;       cvt_pa(s, pa, 0); SBAR();
;       pvh_step<NVT, VRSB, 0, DH, true, 0>(o, vbt, pa, pvf, s);
;       pvh_pro<NVT, VRSB, 1, DH, 0>(vbt, pvf); SBAR();
; #pragma unroll
;       for (int qt = 0; qt < 2; ++qt) { float ps = 0.f;
; #pragma unroll
;         for (int kt = 0; kt < 4; ++kt) ps += (s[kt][qt][0] + s[kt][qt][1]) + (s[kt][qt][2] + s[kt][qt][3]);
;         lp[qt] = lp[qt] * al[qt] + ps; }
;       cvt_pa(s, pa, 1); SBAR();
.LBB0_676:
	v_mul_f32_e32 v196, 0xbdd53b94, v176
	v_fmamk_f32 v197, v142, 0x3dd53b94, v196
	v_mul_f32_e32 v142, 0xbdd53b94, v175
	v_fmamk_f32 v122, v122, 0x3dd53b94, v142
	v_fmamk_f32 v123, v123, 0x3dd53b94, v142
	s_mulk_i32 s36, 0x4800
	v_fmamk_f32 v213, v151, 0x3dd53b94, v196
	v_fmamk_f32 v124, v124, 0x3dd53b94, v142
	v_fmamk_f32 v125, v125, 0x3dd53b94, v142
	v_fmamk_f32 v222, v149, 0x3dd53b94, v142
	v_exp_f32_e32 v149, v122
	v_exp_f32_e32 v151, v123
	v_add_u32_e32 v223, s36, v174
	ds_read_b64_tr_b16 v[122:123], v223 offset:0
	v_fmamk_f32 v126, v126, 0x3dd53b94, v196
	v_fmamk_f32 v127, v127, 0x3dd53b94, v196
	v_fmamk_f32 v217, v153, 0x3dd53b94, v196
	v_exp_f32_e32 v153, v124
	v_exp_f32_e32 v183, v125
	ds_read_b64_tr_b16 v[124:125], v223 offset:0x1200
	v_fmamk_f32 v128, v128, 0x3dd53b94, v196
	v_fmamk_f32 v129, v129, 0x3dd53b94, v196
	v_fmamk_f32 v212, v150, 0x3dd53b94, v196
	v_fmamk_f32 v221, v148, 0x3dd53b94, v142
	v_exp_f32_e32 v148, v126
	v_exp_f32_e32 v150, v127
	ds_read_b64_tr_b16 v[126:127], v223 offset:32
	v_fmamk_f32 v215, v152, 0x3dd53b94, v196
	v_fmamk_f32 v130, v130, 0x3dd53b94, v142
	v_fmamk_f32 v131, v131, 0x3dd53b94, v142
	v_exp_f32_e32 v152, v128
	v_exp_f32_e32 v182, v129
	ds_read_b64_tr_b16 v[128:129], v223 offset:0x1220
	v_fmamk_f32 v132, v132, 0x3dd53b94, v142
	v_fmamk_f32 v133, v133, 0x3dd53b94, v142
	v_exp_f32_e32 v185, v130
	v_exp_f32_e32 v199, v131
	ds_read_b64_tr_b16 v[130:131], v223 offset:64
	v_exp_f32_e32 v201, v132
	v_exp_f32_e32 v203, v133
	ds_read_b64_tr_b16 v[132:133], v223 offset:0x1240
	v_fmamk_f32 v134, v134, 0x3dd53b94, v196
	v_fmamk_f32 v135, v135, 0x3dd53b94, v196
	v_fmamk_f32 v136, v136, 0x3dd53b94, v196
	v_fmamk_f32 v137, v137, 0x3dd53b94, v196
	s_add_i32 s29, s29, 1
	v_fmamk_f32 v143, v143, 0x3dd53b94, v196
	v_fmamk_f32 v205, v144, 0x3dd53b94, v196
	v_fmamk_f32 v207, v145, 0x3dd53b94, v196
	v_fmamk_f32 v209, v138, 0x3dd53b94, v142
	v_fmamk_f32 v211, v139, 0x3dd53b94, v142
	v_fmamk_f32 v214, v140, 0x3dd53b94, v142
	v_fmamk_f32 v216, v141, 0x3dd53b94, v142
	v_fmamk_f32 v219, v146, 0x3dd53b94, v142
	v_fmamk_f32 v220, v147, 0x3dd53b94, v142
	v_exp_f32_e32 v184, v134
	v_exp_f32_e32 v198, v135
	v_exp_f32_e32 v200, v136
	v_exp_f32_e32 v202, v137
	v_cvt_pk_bf16_f32 v134, v148, v150
	v_cvt_pk_bf16_f32 v135, v152, v182
	v_cvt_pk_bf16_f32 v136, v184, v198
	v_cvt_pk_bf16_f32 v137, v200, v202
	v_cvt_pk_bf16_f32 v138, v149, v151
	v_cvt_pk_bf16_f32 v139, v153, v183
	v_cvt_pk_bf16_f32 v140, v185, v199
	v_cvt_pk_bf16_f32 v141, v201, v203
	ds_read_b64_tr_b16 v[144:145], v223 offset:0x60
	ds_read_b64_tr_b16 v[146:147], v223 offset:0x1260
	s_waitcnt lgkmcnt(6)
	v_mfma_f32_16x16x32_bf16 v[58:61], v[134:137], v[122:125], v[58:61]
	v_exp_f32_e32 v204, v197
	v_exp_f32_e32 v206, v143
	v_mfma_f32_16x16x32_bf16 v[62:65], v[138:141], v[122:125], v[62:65]
	ds_read_b64_tr_b16 v[122:123], v223 offset:0x80
	ds_read_b64_tr_b16 v[124:125], v223 offset:0x1280
	s_waitcnt lgkmcnt(6)
	v_mfma_f32_16x16x32_bf16 v[50:53], v[134:137], v[126:129], v[50:53]
	v_exp_f32_e32 v208, v205
	v_exp_f32_e32 v210, v207
	v_mfma_f32_16x16x32_bf16 v[54:57], v[138:141], v[126:129], v[54:57]
	ds_read_b64_tr_b16 v[126:127], v223 offset:0xa0
	ds_read_b64_tr_b16 v[128:129], v223 offset:0x12a0
	s_waitcnt lgkmcnt(6)
	v_mfma_f32_16x16x32_bf16 v[42:45], v[134:137], v[130:133], v[42:45]
	v_exp_f32_e32 v205, v209
	v_exp_f32_e32 v207, v211
	v_mfma_f32_16x16x32_bf16 v[46:49], v[138:141], v[130:133], v[46:49]
	ds_read_b64_tr_b16 v[130:131], v223 offset:0xc0
	ds_read_b64_tr_b16 v[132:133], v223 offset:0x12c0
	s_waitcnt lgkmcnt(6)
	v_mfma_f32_16x16x32_bf16 v[34:37], v[134:137], v[144:147], v[34:37]
	v_exp_f32_e32 v209, v214
	v_exp_f32_e32 v211, v216
	v_mfma_f32_16x16x32_bf16 v[38:41], v[138:141], v[144:147], v[38:41]
	ds_read_b64_tr_b16 v[144:145], v223 offset:0xe0
	ds_read_b64_tr_b16 v[146:147], v223 offset:0x12e0
	s_waitcnt lgkmcnt(6)
	v_mfma_f32_16x16x32_bf16 v[26:29], v[134:137], v[122:125], v[26:29]
	v_exp_f32_e32 v212, v212
	v_exp_f32_e32 v214, v213
	v_mfma_f32_16x16x32_bf16 v[30:33], v[138:141], v[122:125], v[30:33]
	s_waitcnt lgkmcnt(4)
	v_mfma_f32_16x16x32_bf16 v[18:21], v[134:137], v[126:129], v[18:21]
	v_exp_f32_e32 v216, v215
	v_exp_f32_e32 v218, v217
	v_mfma_f32_16x16x32_bf16 v[22:25], v[138:141], v[126:129], v[22:25]
	s_waitcnt lgkmcnt(2)
	v_mfma_f32_16x16x32_bf16 v[10:13], v[134:137], v[130:133], v[10:13]
	v_exp_f32_e32 v213, v219
	v_exp_f32_e32 v215, v220
	v_mfma_f32_16x16x32_bf16 v[14:17], v[138:141], v[130:133], v[14:17]
	s_waitcnt lgkmcnt(0)
	v_mfma_f32_16x16x32_bf16 v[2:5], v[134:137], v[144:147], v[2:5]
	v_exp_f32_e32 v217, v221
	v_exp_f32_e32 v219, v222
	v_mfma_f32_16x16x32_bf16 v[6:9], v[138:141], v[144:147], v[6:9]
	ds_read_b64_tr_b16 v[122:123], v223 offset:0x2400
	ds_read_b64_tr_b16 v[124:125], v223 offset:0x3600
	ds_read_b64_tr_b16 v[126:127], v223 offset:0x2420
	ds_read_b64_tr_b16 v[128:129], v223 offset:0x3620
	ds_read_b64_tr_b16 v[130:131], v223 offset:0x2440
	ds_read_b64_tr_b16 v[132:133], v223 offset:0x3640
	v_add_f32_e64 v134, v148, v150
	v_add_f32_e64 v135, v149, v151
	v_pk_add_f32 v[136:137], v[152:153], v[182:183]
	v_pk_add_f32 v[138:139], v[184:185], v[198:199]
	v_pk_add_f32 v[140:141], v[200:201], v[202:203]
	v_pk_add_f32 v[134:135], v[134:135], v[136:137]
	v_pk_add_f32 v[136:137], v[138:139], v[140:141]
	v_pk_add_f32 v[134:135], v[134:135], 0 op_sel_hi:[1,0]
	v_pk_add_f32 v[138:139], v[208:209], v[210:211]
	v_pk_add_f32 v[134:135], v[136:137], v[134:135]
	v_pk_add_f32 v[136:137], v[204:205], v[206:207]
	v_cvt_pk_bf16_f32 v140, v213, v215
	v_pk_add_f32 v[136:137], v[136:137], v[138:139]
	v_pk_add_f32 v[138:139], v[216:217], v[218:219]
	v_pk_add_f32 v[134:135], v[136:137], v[134:135]
	v_pk_add_f32 v[136:137], v[212:213], v[214:215]
	v_cvt_pk_bf16_f32 v141, v217, v219
	v_pk_add_f32 v[136:137], v[136:137], v[138:139]
	v_cvt_pk_bf16_f32 v138, v205, v207
	v_pk_add_f32 v[134:135], v[136:137], v[134:135]
	v_cvt_pk_bf16_f32 v136, v212, v214
	v_pk_fma_f32 v[156:157], v[156:157], v[168:169], v[134:135]
	v_cvt_pk_bf16_f32 v134, v204, v206
	v_cvt_pk_bf16_f32 v135, v208, v210
	v_cvt_pk_bf16_f32 v137, v216, v218
	v_cvt_pk_bf16_f32 v139, v209, v211
	ds_read_b64_tr_b16 v[144:145], v223 offset:0x2460
	ds_read_b64_tr_b16 v[146:147], v223 offset:0x3660
	s_waitcnt lgkmcnt(6)
; #define SBAR() __builtin_amdgcn_sched_barrier(0)
; #define VLOAD(k0) do { const char* _vb = (const char*)Vh + (size_t)(k0) * (LDV * 2); \
;     _Pragma("unroll") for (int _q = 0; _q < VP; ++_q) sr_.vs[_q] = *reinterpret_cast<const bf16x8*>(_vb + (unsigned)(VROW(_q) * LDV + VC8(_q) * 8) * 2u); } while (0)
; #define VWRITE(bv) do { _Pragma("unroll") for (int _q = 0; _q < VP; ++_q) *(bf16x8*)(V_lds + (bv) * SHM_V + VROW(_q) * VRSB + VC8(_q) * 16) = sr_.vs[_q]; } while (0)
; #define QKT(S, KS) do { if constexpr (QL) qkt16l<DK>(S, KS, Q_lds, c, g); else qkt16<DK>(S, KS, (const bf16x8 (&)[2][DK / 32])qr, c, g); } while (0)
; template <int DK, int DV, int LDQ, int LDK, int LDV, int LDO, typename TOut, bool PIPE, bool QL, bool VS>
; __device__ __forceinline__ void attn_body16(const bf16_t* Qb, const bf16_t* Kh, const bf16_t* Vh, TOut* Ob, int seq, char* lds) {
;     ...
;     for (int j = 0; j < NT; ++j) {
;       const int bsel = j & 1, vsel = VS ? 0 : bsel;
;       if (j + 1 < NT) { VLOAD((j + 1) * KVBLK); KDMA((j + 1) * KVBLK, bsel ^ 1); }
;       SBAR(); QKT(s, K_lds + bsel * SHM_K);
;     ...
;       pvh_step<NVT, VRSB, 1, DH, false, 0>(o, vbt, pa, pvf, s);
;       if constexpr (VS) {
;         asm volatile("s_waitcnt vmcnt(0)" ::: "memory");
;         __syncthreads();
;         if (j + 1 < NT) VWRITE(0);
;       } else if (j + 1 < NT) { asm volatile("s_waitcnt vmcnt(0)" ::: "memory"); VWRITE(bsel ^ 1); }
;       __syncthreads();
	s_nop 0
	v_mfma_f32_16x16x32_bf16 v[58:61], v[134:137], v[122:125], v[58:61]
	v_mfma_f32_16x16x32_bf16 v[62:65], v[138:141], v[122:125], v[62:65]
	ds_read_b64_tr_b16 v[122:123], v223 offset:0x2480
	ds_read_b64_tr_b16 v[124:125], v223 offset:0x3680
	s_waitcnt lgkmcnt(6)
	v_mfma_f32_16x16x32_bf16 v[50:53], v[134:137], v[126:129], v[50:53]
	v_mfma_f32_16x16x32_bf16 v[54:57], v[138:141], v[126:129], v[54:57]
	ds_read_b64_tr_b16 v[126:127], v223 offset:0x24a0
	ds_read_b64_tr_b16 v[128:129], v223 offset:0x36a0
	s_waitcnt lgkmcnt(6)
	v_mfma_f32_16x16x32_bf16 v[42:45], v[134:137], v[130:133], v[42:45]
	v_mfma_f32_16x16x32_bf16 v[46:49], v[138:141], v[130:133], v[46:49]
	ds_read_b64_tr_b16 v[130:131], v223 offset:0x24c0
	ds_read_b64_tr_b16 v[132:133], v223 offset:0x36c0
	s_waitcnt lgkmcnt(6)
	v_mfma_f32_16x16x32_bf16 v[34:37], v[134:137], v[144:147], v[34:37]
	v_mfma_f32_16x16x32_bf16 v[38:41], v[138:141], v[144:147], v[38:41]
	ds_read_b64_tr_b16 v[144:145], v223 offset:0x24e0
	ds_read_b64_tr_b16 v[146:147], v223 offset:0x36e0
	s_waitcnt lgkmcnt(6)
	v_mfma_f32_16x16x32_bf16 v[26:29], v[134:137], v[122:125], v[26:29]
	v_mfma_f32_16x16x32_bf16 v[30:33], v[138:141], v[122:125], v[30:33]
	s_waitcnt lgkmcnt(4)
	v_mfma_f32_16x16x32_bf16 v[18:21], v[134:137], v[126:129], v[18:21]
	v_mfma_f32_16x16x32_bf16 v[22:25], v[138:141], v[126:129], v[22:25]
	s_waitcnt lgkmcnt(2)
	v_mfma_f32_16x16x32_bf16 v[10:13], v[134:137], v[130:133], v[10:13]
	v_mfma_f32_16x16x32_bf16 v[14:17], v[138:141], v[130:133], v[14:17]
	s_waitcnt lgkmcnt(0)
	v_mfma_f32_16x16x32_bf16 v[2:5], v[134:137], v[144:147], v[2:5]
	v_mfma_f32_16x16x32_bf16 v[6:9], v[138:141], v[144:147], v[6:9]
	s_mulk_i32 s33, 0x4800
	s_waitcnt vmcnt(0)
	s_add_i32 s6, s33, 0
	v_add3_u32 v122, s6, v187, v177
	s_waitcnt vmcnt(0)
	ds_write_b128 v122, v[118:121]
	v_add3_u32 v118, s6, v188, v186
	s_add_u32 s52, s52, s80
	s_addc_u32 s53, s53, s81
	s_add_u32 s54, s54, s96
	s_addc_u32 s55, s55, s97
	s_cmp_eq_u32 s30, s29
	ds_write_b128 v118, v[114:117]
	s_waitcnt lgkmcnt(0)
	s_barrier
	s_cbranch_scc1 .LBB0_683
.LBB0_677:
	s_and_b32 s36, s29, 1
	s_xor_b32 s33, s36, 1
	s_mul_i32 s6, s33, 0x6000
	s_add_i32 s6, s6, s28
	s_mov_b32 m0, s6
	global_load_dwordx4 v[118:121], v164, s[54:55]
	s_nop 0
	global_load_dwordx4 v[114:117], v166, s[54:55]
	s_nop 0
	global_load_lds_dwordx4 v158, s[52:53]
	s_add_i32 m0, s6, 0x2000
	s_nop 0
	global_load_lds_dwordx4 v160, s[52:53]
	s_add_i32 m0, s6, 0x4000
	s_nop 0
	global_load_lds_dwordx4 v162, s[52:53]
	s_cmp_lg_u32 s27, -1
	s_mul_i32 s6, s36, 0x6000
	s_cselect_b32 s7, s27, 0
	s_add_i32 s7, s7, s6
	v_add_u32_e32 v122, s7, v189
	v_add_u32_e32 v168, v122, v190
	v_add_u32_e32 v169, v122, v191
	v_add_u32_e32 v182, v122, v192
	v_add_u32_e32 v183, v122, v193
	v_add_u32_e32 v184, v122, v194
	v_add_u32_e32 v185, v122, v195
	ds_read_b128 v[122:125], v168 offset:0
	ds_read_b128 v[126:129], v169 offset:0
	ds_read_b128 v[130:133], v182 offset:0
	ds_read_b128 v[134:137], v183 offset:0
	ds_read_b128 v[138:141], v184 offset:0
	s_waitcnt lgkmcnt(4)
	s_nop 0
	v_mfma_f32_16x16x32_bf16 v[142:145], v[122:125], v[102:105], 0
	v_mfma_f32_16x16x32_bf16 v[122:125], v[122:125], v[110:113], 0
	ds_read_b128 v[146:149], v185 offset:0
	s_waitcnt lgkmcnt(4)
	v_mfma_f32_16x16x32_bf16 v[142:145], v[126:129], v[94:97], v[142:145]
	v_mfma_f32_16x16x32_bf16 v[122:125], v[126:129], v[106:109], v[122:125]
	ds_read_b128 v[150:153], v168 offset:0x1800
	s_waitcnt lgkmcnt(4)
	v_mfma_f32_16x16x32_bf16 v[126:129], v[130:133], v[86:89], v[142:145]
	v_mfma_f32_16x16x32_bf16 v[122:125], v[130:133], v[98:101], v[122:125]
	ds_read_b128 v[130:133], v169 offset:0x1800
	s_waitcnt lgkmcnt(4)
	v_mfma_f32_16x16x32_bf16 v[126:129], v[134:137], v[78:81], v[126:129]
	v_mfma_f32_16x16x32_bf16 v[122:125], v[134:137], v[90:93], v[122:125]
	ds_read_b128 v[134:137], v182 offset:0x1800
	s_waitcnt lgkmcnt(4)
	v_mfma_f32_16x16x32_bf16 v[126:129], v[138:141], v[70:73], v[126:129]
	v_mfma_f32_16x16x32_bf16 v[122:125], v[138:141], v[82:85], v[122:125]
	ds_read_b128 v[138:141], v183 offset:0x1800
	s_waitcnt lgkmcnt(4)
	v_mfma_f32_16x16x32_bf16 v[126:129], v[146:149], v[66:69], v[126:129]
	v_mfma_f32_16x16x32_bf16 v[122:125], v[146:149], v[74:77], v[122:125]
	ds_read_b128 v[142:145], v184 offset:0x1800
	s_waitcnt lgkmcnt(4)
	v_mfma_f32_16x16x32_bf16 v[146:149], v[150:153], v[102:105], 0
	v_mfma_f32_16x16x32_bf16 v[150:153], v[150:153], v[110:113], 0
	ds_read_b128 v[196:199], v185 offset:0x1800
	s_waitcnt lgkmcnt(4)
	v_mfma_f32_16x16x32_bf16 v[146:149], v[130:133], v[94:97], v[146:149]
	v_mfma_f32_16x16x32_bf16 v[130:133], v[130:133], v[106:109], v[150:153]
	ds_read_b128 v[150:153], v168 offset:0x3000
	s_waitcnt lgkmcnt(4)
; __device__ __forceinline__ void partialSM16(f32x4 (&s)[4][2], float (&m_reg)[2], float (&alpha)[2], const float C, const float thr_s) {
;   float pmax[2];
; #pragma unroll
;   for (int qt = 0; qt < 2; ++qt) { float v = s[0][qt][0];
; #pragma unroll
;     for (int kt = 0; kt < 4; ++kt)
; #pragma unroll
;       for (int r = 0; r < 4; ++r) v = fmaxf(v, s[kt][qt][r]);
;     pmax[qt] = xmax4(v); }
;   float mn[2];
;   if (__builtin_expect(__all(pmax[0] - m_reg[0] <= thr_s && pmax[1] - m_reg[1] <= thr_s), 1)) { mn[0] = m_reg[0]; mn[1] = m_reg[1]; alpha[0] = 1.f; alpha[1] = 1.f; }
;   else {
; #pragma unroll
;     for (int qt = 0; qt < 2; ++qt) { mn[qt] = fmaxf(m_reg[qt], pmax[qt]); alpha[qt] = __builtin_amdgcn_exp2f((m_reg[qt] - mn[qt]) * C); m_reg[qt] = mn[qt]; } }
	v_mfma_f32_16x16x32_bf16 v[146:149], v[134:137], v[86:89], v[146:149]
	v_mfma_f32_16x16x32_bf16 v[130:133], v[134:137], v[98:101], v[130:133]
	ds_read_b128 v[200:203], v169 offset:0x3000
	s_waitcnt lgkmcnt(4)
	v_mfma_f32_16x16x32_bf16 v[134:137], v[138:141], v[78:81], v[146:149]
	v_mfma_f32_16x16x32_bf16 v[130:133], v[138:141], v[90:93], v[130:133]
	ds_read_b128 v[138:141], v182 offset:0x3000
	s_waitcnt lgkmcnt(4)
	v_mfma_f32_16x16x32_bf16 v[134:137], v[142:145], v[70:73], v[134:137]
	v_mfma_f32_16x16x32_bf16 v[130:133], v[142:145], v[82:85], v[130:133]
	ds_read_b128 v[142:145], v183 offset:0x3000
	s_waitcnt lgkmcnt(4)
	v_mfma_f32_16x16x32_bf16 v[134:137], v[196:199], v[66:69], v[134:137]
	v_mfma_f32_16x16x32_bf16 v[130:133], v[196:199], v[74:77], v[130:133]
	ds_read_b128 v[146:149], v184 offset:0x3000
	s_waitcnt lgkmcnt(4)
	v_mfma_f32_16x16x32_bf16 v[196:199], v[150:153], v[102:105], 0
	v_mfma_f32_16x16x32_bf16 v[150:153], v[150:153], v[110:113], 0
	ds_read_b128 v[204:207], v185 offset:0x3000
	s_waitcnt lgkmcnt(4)
	v_mfma_f32_16x16x32_bf16 v[196:199], v[200:203], v[94:97], v[196:199]
	v_mfma_f32_16x16x32_bf16 v[150:153], v[200:203], v[106:109], v[150:153]
	ds_read_b128 v[200:203], v168 offset:0x4800
	s_waitcnt lgkmcnt(4)
	v_mfma_f32_16x16x32_bf16 v[196:199], v[138:141], v[86:89], v[196:199]
	v_mfma_f32_16x16x32_bf16 v[138:141], v[138:141], v[98:101], v[150:153]
	ds_read_b128 v[150:153], v169 offset:0x4800
	s_waitcnt lgkmcnt(4)
	v_mfma_f32_16x16x32_bf16 v[196:199], v[142:145], v[78:81], v[196:199]
	v_mfma_f32_16x16x32_bf16 v[138:141], v[142:145], v[90:93], v[138:141]
	ds_read_b128 v[208:211], v182 offset:0x4800
	s_waitcnt lgkmcnt(4)
	v_mfma_f32_16x16x32_bf16 v[142:145], v[146:149], v[70:73], v[196:199]
	v_mfma_f32_16x16x32_bf16 v[138:141], v[146:149], v[82:85], v[138:141]
	ds_read_b128 v[146:149], v183 offset:0x4800
	s_waitcnt lgkmcnt(4)
	v_mfma_f32_16x16x32_bf16 v[142:145], v[204:207], v[66:69], v[142:145]
	v_mfma_f32_16x16x32_bf16 v[138:141], v[204:207], v[74:77], v[138:141]
	ds_read_b128 v[196:199], v184 offset:0x4800
	s_waitcnt lgkmcnt(4)
	v_mfma_f32_16x16x32_bf16 v[204:207], v[200:203], v[102:105], 0
	v_mfma_f32_16x16x32_bf16 v[200:203], v[200:203], v[110:113], 0
	ds_read_b128 v[212:215], v185 offset:0x4800
	s_waitcnt lgkmcnt(4)
	v_mfma_f32_16x16x32_bf16 v[204:207], v[150:153], v[94:97], v[204:207]
	v_mfma_f32_16x16x32_bf16 v[150:153], v[150:153], v[106:109], v[200:203]
	s_waitcnt lgkmcnt(3)
	v_mfma_f32_16x16x32_bf16 v[150:153], v[208:211], v[98:101], v[150:153]
	v_mfma_f32_16x16x32_bf16 v[200:203], v[208:211], v[86:89], v[204:207]
	s_waitcnt lgkmcnt(2)
	v_mfma_f32_16x16x32_bf16 v[200:203], v[146:149], v[78:81], v[200:203]
	v_mfma_f32_16x16x32_bf16 v[146:149], v[146:149], v[90:93], v[150:153]
	s_waitcnt lgkmcnt(1)
	v_mfma_f32_16x16x32_bf16 v[150:153], v[196:199], v[70:73], v[200:203]
	v_mfma_f32_16x16x32_bf16 v[146:149], v[196:199], v[82:85], v[146:149]
	s_waitcnt lgkmcnt(0)
	v_mfma_f32_16x16x32_bf16 v[150:153], v[212:215], v[66:69], v[150:153]
	v_mfma_f32_16x16x32_bf16 v[146:149], v[212:215], v[74:77], v[146:149]
	s_nop 1
	v_max_f32_e32 v168, v126, v127
	v_max3_f32 v168, v168, v128, v129
	v_max3_f32 v168, v168, v134, v135
	v_max3_f32 v168, v168, v136, v137
	v_max3_f32 v168, v168, v142, v143
	v_max3_f32 v168, v168, v144, v145
	v_max3_f32 v168, v168, v150, v151
	v_max3_f32 v168, v168, v152, v153
	v_mov_b32_e32 v169, v168
	s_nop 1
	v_permlane16_swap_b32_e32 v168, v169
	v_max_f32_e32 v168, v168, v169
	v_mov_b32_e32 v169, v168
	s_nop 1
	v_permlane32_swap_b32_e32 v168, v169
	v_max_f32_e32 v169, v168, v169
	s_nop 1
	v_max_f32_e32 v168, v122, v123
	v_max3_f32 v168, v168, v124, v125
	v_max3_f32 v168, v168, v130, v131
	v_max3_f32 v168, v168, v132, v133
	v_max3_f32 v168, v168, v138, v139
	v_max3_f32 v168, v168, v140, v141
	v_max3_f32 v168, v168, v146, v147
	v_max3_f32 v168, v168, v148, v149
	v_mov_b32_e32 v182, v168
	s_nop 1
	v_permlane16_swap_b32_e32 v168, v182
	v_max_f32_e32 v168, v168, v182
	v_mov_b32_e32 v182, v168
	s_nop 1
	v_permlane32_swap_b32_e32 v168, v182
	v_max_f32_e32 v196, v168, v182
	v_sub_f32_e32 v168, v169, v176
	v_cmp_ge_f32_e32 vcc, s49, v168
	v_sub_f32_e32 v168, v196, v175
	v_cmp_ge_f32_e64 s[6:7], s49, v168
	s_and_b64 s[6:7], vcc, s[6:7]
	s_cmp_eq_u64 s[6:7], exec
	v_mov_b32_e32 v168, 1.0
	s_cbranch_scc0 .LBB0_682
	v_mov_b32_e32 v169, 1.0
.LBB0_679:
	v_min_f32_e32 v182, v168, v169
	v_cmp_gt_f32_e32 vcc, 1.0, v182
	s_cbranch_vccz .LBB0_676
	s_and_saveexec_b64 s[6:7], s[4:5]
	s_cbranch_execz .LBB0_675
	ds_write2_b32 v173, v168, v169 offset0:32 offset1:48
	s_branch .LBB0_675

; #define SBAR() __builtin_amdgcn_sched_barrier(0)
; #define SWRITE(b) SWRITE2(b, b)
; #define SWAIT() asm volatile("s_waitcnt vmcnt(0)" ::: "memory")
; template <int DK, int DV, int LDQ, int LDK, int LDV, int LDO, typename TOut, bool PIPE, bool QL, bool VS>
; __device__ __forceinline__ void attn_body16(const bf16_t* Qb, const bf16_t* Kh, const bf16_t* Vh, TOut* Ob, int seq, char* lds) {
;     ...
;     for (int ks = 0; ks < DK / 32; ++ks) { const bf16x8 qv = *reinterpret_cast<const bf16x8*>(Qb + (long)(wid * QBLK + qt * 16 + c) * LDQ + ks * 32 + g * 8);
;       if constexpr (QL) { *reinterpret_cast<bf16x8*>(Q_lds + (qt * 16 + c) * (DK * 2) + (((ks * 32 + g * 8) * 2) ^ ((c & 7) << 4))) = qv; if (qt == 0 && ks == 0) qr[0][0] = qv; } else qr[qt][ks] = qv; }
;     ...
;   const int vb0 = (int)(uintptr_t)V_lds + (4 * g + (c >> 2)) * VRSB + (c & 3) * 8;
;   struct { bf16x8 vs[VP], ks[PIPE ? KP : 1]; } sr_;
;   const int widu = __builtin_amdgcn_readfirstlane(wid);
;     ...
;   bf16x8 pa[2][2]; const int NT = seq / KVBLK;
;   if constexpr (PIPE) {
;     f32x4 sA[4][2], sB[4][2]; float alA[2], alB[2];
;     SLOAD(0); asm volatile("s_waitcnt vmcnt(0)" ::: "memory"); SWRITE(0); __syncthreads();
;     QKT(sA, K_lds); partialSM16(sA, m_reg, alA, C, THR_S);
;     SLOAD(KVBLK);
;     SWAIT(); SWRITE(1); __syncthreads();
;     for (int j = 1; j + 1 < NT; j += 2) {
;       SLOAD((j + 1) * KVBLK); SBAR(); QKT(sB, K_lds + SHM_K); SBAR();
;       finishSM16(sA, alA, lp, pa); SBAR();
;       pv16<NVT, VRSB>(o, vb0, pa); partialSM16(sB, m_reg, alB, C, THR_S);
;       __syncthreads(); SWAIT(); SWRITE(0);
;       RESC(alB); __syncthreads();
;       SLOAD((j + 2) * KVBLK); SBAR(); QKT(sA, K_lds); SBAR();
;       finishSM16(sB, alB, lp, pa); SBAR();
;       pv16<NVT, VRSB>(o, vb0 + (int)SHM_V, pa); partialSM16(sA, m_reg, alA, C, THR_S);
;       __syncthreads(); SWAIT(); SWRITE(1);
;       RESC(alA); __syncthreads();
;     }
;     SBAR(); QKT(sB, K_lds + SHM_K); SBAR();
;     finishSM16(sA, alA, lp, pa); SBAR();
;     pv16<NVT, VRSB>(o, vb0, pa); partialSM16(sB, m_reg, alB, C, THR_S);
;     __syncthreads(); RESC(alB);
;     finishSM16(sB, alB, lp, pa); SBAR();
;     pv16<NVT, VRSB>(o, vb0 + (int)SHM_V, pa);
;   } else {
;     f32x4 s[4][2]; float al[2];
;     VLOAD(0); KDMA(0, 0); asm volatile("s_waitcnt vmcnt(0)" ::: "memory"); VWRITE(0); __syncthreads();
.LBB0_698:
	s_ashr_i32 s11, s10, 3
	s_and_b32 s26, s10, 1
	s_mul_i32 s7, s11, 0x1100
	s_mul_hi_i32 s6, s11, 0x1100
	s_add_u32 s8, s7, s4
	s_addc_u32 s9, s6, s5
	s_mul_i32 s4, s9, 0x3080
	s_mul_hi_u32 s5, s8, 0x3080
	s_add_i32 s5, s5, s4
	s_mul_i32 s4, s8, 0x3080
	s_add_u32 s4, s1, s4
	s_addc_u32 s5, s16, s5
	s_lshl_b32 s6, s10, 7
	s_and_b32 s27, s6, 0x300
	s_lshl_b32 s12, s27, 1
	s_add_u32 s4, s4, s12
	s_addc_u32 s5, s5, 0
	s_lshl_b32 s6, s26, 8
	v_mov_b32_e32 v37, v0
	s_add_u32 s4, s4, s6
	s_addc_u32 s5, s5, 0
	v_bfe_u32 v252, v37, 4, 2
	v_ashrrev_i32_e32 v187, 6, v37
	v_lshlrev_b32_e32 v34, 4, v252
	v_mov_b32_e32 v35, v179
	v_and_b32_e32 v253, 15, v37
	v_lshlrev_b32_e32 v186, 5, v187
	v_lshl_add_u64 v[2:3], s[4:5], 0, v[34:35]
	s_mov_b64 s[4:5], 0x1800
	v_or_b32_e32 v20, v186, v253
	v_lshl_add_u64 v[18:19], v[2:3], 0, s[4:5]
	v_mad_i64_i32 v[14:15], s[4:5], v20, s84, v[18:19]
	global_load_dwordx4 v[2:5], v[14:15], off
	global_load_dwordx4 v[6:9], v[14:15], off offset:64
	v_or_b32_e32 v20, 16, v20
	v_mad_i64_i32 v[30:31], s[4:5], v20, s84, v[18:19]
	global_load_dwordx4 v[10:13], v[14:15], off offset:128
	s_nop 0
	global_load_dwordx4 v[14:17], v[14:15], off offset:192
	s_nop 0
	global_load_dwordx4 v[18:21], v[30:31], off
	global_load_dwordx4 v[22:25], v[30:31], off offset:64
	global_load_dwordx4 v[26:29], v[30:31], off offset:128
	s_nop 0
	global_load_dwordx4 v[30:33], v[30:31], off offset:192
	s_mul_hi_i32 s7, s11, 0x3388000
	s_mul_i32 s11, s11, 0x3388000
	s_add_u32 s4, s1, s11
	s_addc_u32 s5, s16, s7
	s_add_u32 s12, s4, s12
	s_addc_u32 s13, s5, 0
	s_add_u32 s4, s12, s6
	s_addc_u32 s5, s13, 0
	s_add_u32 s4, s4, 0x2000
	s_addc_u32 s5, s5, 0
	s_add_u32 s12, s12, 0x2800
	s_addc_u32 s13, s13, 0
	v_and_b32_e32 v36, 0x3fffffc0, v37
	s_add_i32 s33, 0, 0x20800
	v_ashrrev_i32_e32 v49, 31, v37
	v_lshl_add_u32 v45, v36, 2, s33
	v_lshrrev_b32_e32 v36, 27, v49
	v_add_u32_e32 v36, v37, v36
	v_ashrrev_i32_e32 v52, 5, v36
	v_and_b32_e32 v36, 0xfffffe0, v36
	v_sub_u32_e32 v36, v37, v36
	v_lshlrev_b32_e32 v36, 4, v36
	v_add_u32_e32 v53, 0x200, v37
	v_mad_u64_u32 v[38:39], s[36:37], v52, s84, v[36:37]
	v_ashrrev_i32_e32 v54, 31, v53
	v_lshrrev_b32_e32 v39, 27, v54
	v_add_u32_e32 v39, v53, v39
	v_ashrrev_i32_e32 v55, 5, v39
	v_and_b32_e32 v39, 0xfffffe0, v39
	v_sub_u32_e32 v39, v53, v39
	v_lshlrev_b32_e32 v41, 13, v187
	v_lshlrev_b32_e32 v40, 4, v39
	v_mad_u64_u32 v[42:43], s[36:37], v55, s84, v[40:41]
	v_add_u32_e32 v39, 0x400, v37
	v_ashrrev_i32_e32 v43, 31, v39
	v_lshrrev_b32_e32 v43, 27, v43
	v_add_u32_e32 v43, v39, v43
	v_ashrrev_i32_e32 v56, 5, v43
	v_and_b32_e32 v43, 0xfffffe0, v43
	v_sub_u32_e32 v39, v39, v43
	v_lshlrev_b32_e32 v44, 4, v39
	v_add_u32_e32 v39, 0x600, v37
	v_ashrrev_i32_e32 v43, 31, v39
	v_lshrrev_b32_e32 v43, 27, v43
	v_add_u32_e32 v43, v39, v43
	v_ashrrev_i32_e32 v57, 5, v43
	v_and_b32_e32 v43, 0xfffffe0, v43
	v_lshrrev_b32_e32 v35, 4, v37
	s_add_i32 s30, 0, 0x10800
	v_sub_u32_e32 v39, v39, v43
	v_lshlrev_b32_e32 v214, 8, v253
	v_and_b32_e32 v43, 7, v37
	v_add3_u32 v41, s30, v41, v214
	v_bitop3_b32 v35, v35, v43, 3 bitop3:0x6c
	v_lshlrev_b32_e32 v48, 4, v39
	v_lshlrev_b32_e32 v39, 4, v37
	v_lshl_add_u32 v35, v35, 4, v41
	global_load_dwordx4 v[66:69], v38, s[12:13]
	global_load_dwordx4 v[70:73], v42, s[12:13]
	v_and_b32_e32 v39, 0x70, v39
	v_mad_u64_u32 v[46:47], s[36:37], v56, s84, v[44:45]
	v_mad_u64_u32 v[50:51], s[36:37], v57, s84, v[48:49]
	global_load_dwordx4 v[74:77], v46, s[12:13]
	global_load_dwordx4 v[78:81], v50, s[12:13]
	s_cmp_lg_u32 0, -1
	s_cselect_b32 s12, 0, 0
	v_readfirstlane_b32 s13, v187
	s_lshl_b32 s33, s13, 10
	s_add_i32 s30, 0, 0x8800
	s_cmp_lg_u32 s30, -1
	s_waitcnt vmcnt(11)
	ds_write_b128 v35, v[2:5]
	v_or_b32_e32 v2, 64, v34
	v_or_b32_e32 v3, 0x80, v34
	v_or_b32_e32 v4, 0xc0, v34
	v_xad_u32 v2, v2, v39, v41
	v_xad_u32 v3, v3, v39, v41
	v_xad_u32 v4, v4, v39, v41
	s_waitcnt vmcnt(10)
	ds_write_b128 v2, v[6:9]
	s_waitcnt vmcnt(9)
	ds_write_b128 v3, v[10:13]
	s_waitcnt vmcnt(8)
	ds_write_b128 v4, v[14:17]
	s_waitcnt vmcnt(7)
	ds_write_b128 v35, v[18:21] offset:4096
	s_waitcnt vmcnt(6)
	ds_write_b128 v2, v[22:25] offset:4096
	s_waitcnt vmcnt(5)
	ds_write_b128 v3, v[26:29] offset:4096
	s_waitcnt vmcnt(4)
; #define SBAR() __builtin_amdgcn_sched_barrier(0)
; #define SWRITE(b, i) do { *(bf16x8*)(V_lds + (b) * SHM_V + vst0) = sr_[i].vs0; *(bf16x8*)(V_lds + (b) * SHM_V + vst1) = sr_[i].vs1; \
;     _Pragma("unroll") for (int _q = 0; _q < KP; ++_q) *(bf16x8*)(K_lds + (b) * SHM_K + KROW(_q) * (DK * 2) + ((KC8(_q) * 16) ^ ((KROW(_q) & 7) << 4))) = sr_[i].ks[_q]; } while (0)
; #define SWAIT() do { if constexpr (SDEPTH == 2) asm volatile("s_waitcnt vmcnt(4)" ::: "memory"); else asm volatile("s_waitcnt vmcnt(0)" ::: "memory"); } while (0)
; #define SWRITE(b) SWRITE2(b, b)
; template <int DK, int DV, int LDQ, int LDK, int LDV, int LDO, typename TOut, bool PIPE, bool QL, bool VS>
; __device__ __forceinline__ void attn_body16(const bf16_t* Qb, const bf16_t* Kh, const bf16_t* Vh, TOut* Ob, int seq, char* lds) {
;     ...
;   const int vb0 = (int)(uintptr_t)V_lds + (4 * g + (c >> 2)) * VRSB + (c & 3) * 8;
;   struct { bf16x8 vs[VP], ks[PIPE ? KP : 1]; } sr_;
;   const int widu = __builtin_amdgcn_readfirstlane(wid);
;     ...
;   bf16x8 pa[2][2]; const int NT = seq / KVBLK;
;   if constexpr (PIPE) {
;     f32x4 sA[4][2], sB[4][2]; float alA[2], alB[2];
;     SLOAD(0); asm volatile("s_waitcnt vmcnt(0)" ::: "memory"); SWRITE(0); __syncthreads();
;     QKT(sA, K_lds); partialSM16(sA, m_reg, alA, C, THR_S);
;     SLOAD(KVBLK);
;     SWAIT(); SWRITE(1); __syncthreads();
;     for (int j = 1; j + 1 < NT; j += 2) {
;       SLOAD((j + 1) * KVBLK); SBAR(); QKT(sB, K_lds + SHM_K); SBAR();
;       finishSM16(sA, alA, lp, pa); SBAR();
;       pv16<NVT, VRSB>(o, vb0, pa); partialSM16(sB, m_reg, alB, C, THR_S);
;       __syncthreads(); SWAIT(); SWRITE(0);
;       RESC(alB); __syncthreads();
;       SLOAD((j + 2) * KVBLK); SBAR(); QKT(sA, K_lds); SBAR();
;       finishSM16(sB, alB, lp, pa); SBAR();
;       pv16<NVT, VRSB>(o, vb0 + (int)SHM_V, pa); partialSM16(sA, m_reg, alA, C, THR_S);
;       __syncthreads(); SWAIT(); SWRITE(1);
;       RESC(alA); __syncthreads();
;     }
;     SBAR(); QKT(sB, K_lds + SHM_K); SBAR();
;     finishSM16(sA, alA, lp, pa); SBAR();
;     pv16<NVT, VRSB>(o, vb0, pa); partialSM16(sB, m_reg, alB, C, THR_S);
;     __syncthreads(); RESC(alB);
;     finishSM16(sB, alB, lp, pa); SBAR();
;     pv16<NVT, VRSB>(o, vb0 + (int)SHM_V, pa);
;   } else {
;     f32x4 s[4][2]; float al[2];
;     VLOAD(0); KDMA(0, 0); asm volatile("s_waitcnt vmcnt(0)" ::: "memory"); VWRITE(0); __syncthreads();
	ds_write_b128 v4, v[30:33] offset:4096
	v_bfe_u32 v2, v37, 2, 2
	v_lshl_or_b32 v2, v252, 2, v2
	v_lshlrev_b32_e32 v3, 3, v37
	v_and_b32_e32 v3, 24, v3
	v_mul_u32_u24_e32 v2, 0x220, v2
	v_add3_u32 v216, v3, s12, v2
	v_lshrrev_b32_e32 v2, 28, v49
	v_add_u32_e32 v2, v37, v2
	v_lshrrev_b32_e32 v4, 28, v54
	v_ashrrev_i32_e32 v3, 4, v2
	v_and_b32_e32 v2, 0xffffff0, v2
	v_add_u32_e32 v4, v53, v4
	s_cselect_b32 s12, s30, 0
	v_sub_u32_e32 v2, v37, v2
	v_ashrrev_i32_e32 v5, 4, v4
	v_and_b32_e32 v4, 0xffffff0, v4
	s_add_i32 s33, s33, s12
	v_bitop3_b32 v2, v3, v2, 7 bitop3:0x6c
	v_mul_lo_u32 v3, v3, s84
	v_sub_u32_e32 v4, v53, v4
	v_lshl_add_u32 v2, v2, 4, v3
	s_mov_b32 m0, s33
	v_bitop3_b32 v4, v5, v4, 7 bitop3:0x6c
	v_mul_lo_u32 v5, v5, s84
	global_load_lds_dwordx4 v2, s[4:5]
	v_lshl_add_u32 v4, v4, 4, v5
	s_add_i32 m0, s33, 0x2000
	v_mul_lo_u32 v6, v52, s86
	global_load_lds_dwordx4 v4, s[4:5]
	v_add_u32_e32 v6, 0, v6
	v_add_u32_e32 v217, v6, v36
	v_mul_lo_u32 v6, v55, s86
	v_add_u32_e32 v6, 0, v6
	s_lshl_b32 s10, s10, 8
	v_add_u32_e32 v218, v6, v40
	v_mul_lo_u32 v6, v56, s86
	s_and_b32 s10, s10, 0x600
	v_add_u32_e32 v6, 0, v6
	s_or_b32 s12, s11, s10
	v_add_u32_e32 v220, v6, v44
	v_mul_lo_u32 v6, v57, s86
	s_add_u32 s10, s21, s12
	v_add_u32_e32 v6, 0, v6
	v_lshlrev_b32_e32 v178, 4, v253
	s_movk_i32 s4, 0x70
	s_addc_u32 s11, s22, s7
	s_or_b32 s6, s12, s6
	v_add_u32_e32 v221, v6, v48
	v_and_b32_e32 v6, 0x70, v178
	v_bitop3_b32 v222, v34, v178, s4 bitop3:0x78
	s_movk_i32 s4, 0xc0
	s_add_u32 s6, s23, s6
	v_mov_b32_e32 v39, v179
	v_mov_b32_e32 v43, v179
	v_mov_b32_e32 v47, v179
	v_mov_b32_e32 v51, v179
	v_mov_b32_e32 v3, v179
	v_mov_b32_e32 v5, v179
	s_waitcnt vmcnt(0)
	v_bitop3_b32 v224, v34, v6, 64 bitop3:0x36
	v_bitop3_b32 v226, v34, v6, s14 bitop3:0x36
	v_bitop3_b32 v228, v34, v6, s4 bitop3:0x36
	s_addc_u32 s7, s24, s7
	v_mov_b32_e32 v18, v179
	v_mov_b32_e32 v19, v179
	v_mov_b32_e32 v20, v179
	v_mov_b32_e32 v21, v179
	v_add_u32_e32 v223, v41, v222
	v_add_u32_e32 v225, v41, v224
	v_add_u32_e32 v227, v41, v226
	v_add_u32_e32 v229, v41, v228
	v_lshl_add_u32 v219, v253, 2, v45
	v_add_u32_e32 v215, v45, v34
	s_mov_b64 s[56:57], s[10:11]
	s_mov_b64 s[58:59], s[6:7]
	v_mov_b32_e32 v188, v38
	v_mov_b32_e32 v190, v42
	v_mov_b32_e32 v192, v46
	v_mov_b32_e32 v194, v50
	v_mov_b32_e32 v198, v2
	v_mov_b32_e32 v200, v4
	v_mov_b32_e32 v196, 0
	v_mov_b64_e32 v[84:85], v[20:21]
	v_mov_b64_e32 v[88:89], v[20:21]
	v_mov_b64_e32 v[92:93], v[20:21]
	v_mov_b64_e32 v[96:97], v[20:21]
	v_mov_b64_e32 v[100:101], v[20:21]
	v_mov_b64_e32 v[104:105], v[20:21]
	v_mov_b64_e32 v[108:109], v[20:21]
	v_mov_b64_e32 v[112:113], v[20:21]
	v_mov_b64_e32 v[36:37], v[20:21]
	v_mov_b64_e32 v[40:41], v[20:21]
	v_mov_b64_e32 v[44:45], v[20:21]
	v_mov_b64_e32 v[48:49], v[20:21]
	v_mov_b64_e32 v[52:53], v[20:21]
	v_mov_b64_e32 v[56:57], v[20:21]
	v_mov_b64_e32 v[60:61], v[20:21]
	v_mov_b64_e32 v[64:65], v[20:21]
	v_mov_b64_e32 v[116:117], v[20:21]
	v_mov_b64_e32 v[120:121], v[20:21]
	v_mov_b64_e32 v[124:125], v[20:21]
	v_mov_b64_e32 v[128:129], v[20:21]
	v_mov_b64_e32 v[132:133], v[20:21]
	v_mov_b64_e32 v[136:137], v[20:21]
	v_mov_b64_e32 v[140:141], v[20:21]
	v_mov_b64_e32 v[144:145], v[20:21]
	v_mov_b64_e32 v[32:33], v[20:21]
	v_mov_b64_e32 v[28:29], v[20:21]
	v_mov_b64_e32 v[24:25], v[20:21]
	v_mov_b64_e32 v[14:15], v[18:19]
	v_mov_b64_e32 v[10:11], v[18:19]
	v_mov_b64_e32 v[6:7], v[18:19]
	v_mov_b64_e32 v[2:3], v[18:19]
	s_mov_b32 s29, 1
	v_cmp_eq_u32_e64 s[4:5], 0, v252
	v_mov_b32_e32 v230, 0xf149f2ca
	s_mov_b64 s[10:11], 0
	v_mov_b64_e32 v[82:83], v[18:19]
	v_mov_b64_e32 v[86:87], v[18:19]
	v_mov_b64_e32 v[90:91], v[18:19]
	v_mov_b64_e32 v[94:95], v[18:19]
	v_mov_b64_e32 v[98:99], v[18:19]
	v_mov_b64_e32 v[102:103], v[18:19]
	v_mov_b64_e32 v[106:107], v[18:19]
	v_mov_b64_e32 v[110:111], v[18:19]
	v_mov_b64_e32 v[34:35], v[18:19]
	v_mov_b64_e32 v[38:39], v[18:19]
	v_mov_b64_e32 v[42:43], v[18:19]
	v_mov_b64_e32 v[46:47], v[18:19]
	v_mov_b64_e32 v[50:51], v[18:19]
	v_mov_b64_e32 v[54:55], v[18:19]
	v_mov_b64_e32 v[58:59], v[18:19]
	v_mov_b64_e32 v[62:63], v[18:19]
	v_mov_b64_e32 v[114:115], v[18:19]
	v_mov_b64_e32 v[118:119], v[18:19]
	v_mov_b64_e32 v[122:123], v[18:19]
	v_mov_b64_e32 v[126:127], v[18:19]
	v_mov_b64_e32 v[130:131], v[18:19]
	v_mov_b64_e32 v[134:135], v[18:19]
	v_mov_b64_e32 v[138:139], v[18:19]
	v_mov_b64_e32 v[142:143], v[18:19]
	v_mov_b64_e32 v[30:31], v[18:19]
	v_mov_b64_e32 v[26:27], v[18:19]
	v_mov_b64_e32 v[22:23], v[18:19]
	v_mov_b64_e32 v[16:17], v[20:21]
	v_mov_b64_e32 v[12:13], v[20:21]
	v_mov_b64_e32 v[8:9], v[20:21]
	v_mov_b64_e32 v[4:5], v[20:21]
	v_mov_b32_e32 v231, 0xf149f2ca
	v_mov_b32_e32 v197, v196
	s_waitcnt vmcnt(0)
	ds_write_b128 v217, v[66:69]
	ds_write_b128 v218, v[70:73]
	ds_write_b128 v220, v[74:77]
	ds_write_b128 v221, v[78:81]
	s_waitcnt lgkmcnt(0)
	s_barrier
	s_branch .LBB0_700

; #define SBAR() __builtin_amdgcn_sched_barrier(0)
; #define VLOAD(k0) do { const char* _vb = (const char*)Vh + (size_t)(k0) * (LDV * 2); \
;     _Pragma("unroll") for (int _q = 0; _q < VP; ++_q) sr_.vs[_q] = *reinterpret_cast<const bf16x8*>(_vb + (unsigned)(VROW(_q) * LDV + VC8(_q) * 8) * 2u); } while (0)
; #define QKT(S, KS) do { if constexpr (QL) qkt16l<DK>(S, KS, Q_lds, c, g); else qkt16<DK>(S, KS, (const bf16x8 (&)[2][DK / 32])qr, c, g); } while (0)
; template <int DK>
; __device__ __forceinline__ void qkt16l(f32x4 (&s)[4][2], const char* Ks, const char* Qs, int c, int g) {
;   constexpr int D = 3; int qad[DK / 32], kad[DK / 32]; bf16x8 qa[2][2], fr[D + 1];
;   const int kb = (int)(uintptr_t)Ks + c * (DK * 2), qb = (int)(uintptr_t)Qs + c * (DK * 2);
; #pragma unroll
;   for (int ks = 0; ks < DK / 32; ++ks) { const int sw = ((ks * 32 + g * 8) * 2) ^ ((c & 7) << 4); kad[ks] = kb + sw; qad[ks] = qb + sw; }
;   ql_issue<DK, D, 0, 2 + D>(qa, fr, qad, kad);
;   ql_step<DK, D, 0>(s, qa, fr, qad, kad);
; }
; __device__ __forceinline__ void partialSM16(f32x4 (&s)[4][2], float (&m_reg)[2], float (&alpha)[2], const float C, const float thr_s) {
;   float pmax[2];
; #pragma unroll
;   for (int qt = 0; qt < 2; ++qt) { float v = s[0][qt][0];
; #pragma unroll
;     for (int kt = 0; kt < 4; ++kt)
; #pragma unroll
;       for (int r = 0; r < 4; ++r) v = fmaxf(v, s[kt][qt][r]);
;     pmax[qt] = xmax4(v); }
;   float mn[2];
;   if (__builtin_expect(__all(pmax[0] - m_reg[0] <= thr_s && pmax[1] - m_reg[1] <= thr_s), 1)) { mn[0] = m_reg[0]; mn[1] = m_reg[1]; alpha[0] = 1.f; alpha[1] = 1.f; }
;   else {
; #pragma unroll
;     for (int qt = 0; qt < 2; ++qt) { mn[qt] = fmaxf(m_reg[qt], pmax[qt]); alpha[qt] = __builtin_amdgcn_exp2f((m_reg[qt] - mn[qt]) * C); m_reg[qt] = mn[qt]; } }
; template <int DK, int DV, int LDQ, int LDK, int LDV, int LDO, typename TOut, bool PIPE, bool QL, bool VS>
; __device__ __forceinline__ void attn_body16(const bf16_t* Qb, const bf16_t* Kh, const bf16_t* Vh, TOut* Ob, int seq, char* lds) {
;     ...
;     for (int j = 0; j < NT; ++j) {
;       const int bsel = j & 1, vsel = VS ? 0 : bsel;
;       if (j + 1 < NT) { VLOAD((j + 1) * KVBLK); KDMA((j + 1) * KVBLK, bsel ^ 1); }
;       SBAR(); QKT(s, K_lds + bsel * SHM_K);
;       partialSM16(s, m_reg, al, C, THR_S);
.LBB0_702:
	s_andn2_b64 vcc, exec, s[6:7]
	s_cbranch_vccnz .LBB0_704
	s_lshl_b32 s36, s37, 14
	s_xor_b32 s6, s36, 0x4000
	s_add_i32 s6, s6, s33
	s_add_u32 s52, s56, s10
	s_addc_u32 s53, s57, s11
	s_add_u32 s54, s58, s10
	s_addc_u32 s55, s59, s11
	s_mov_b32 m0, s6
	global_load_dwordx4 v[66:69], v188, s[52:53]
	s_nop 0
	global_load_dwordx4 v[70:73], v190, s[52:53]
	s_nop 0
	global_load_dwordx4 v[74:77], v192, s[52:53]
	s_nop 0
	global_load_dwordx4 v[78:81], v194, s[52:53]
	s_nop 0
	global_load_lds_dwordx4 v198, s[54:55]
	s_add_i32 m0, s6, 0x2000
	s_nop 0
	global_load_lds_dwordx4 v200, s[54:55]
.LBB0_704:
	s_cmp_lg_u32 s30, -1
	s_cselect_b32 s6, s30, 0
	s_add_i32 s6, s6, s36
	v_add_u32_e32 v146, s6, v214
	v_add_u32_e32 v170, v146, v222
	v_add_u32_e32 v182, v146, v224
	v_add_u32_e32 v183, v146, v226
	v_add_u32_e32 v1, v146, v228
	ds_read_b128 v[146:149], v223 offset:0
	ds_read_b128 v[150:153], v223 offset:0x1000
	ds_read_b128 v[154:157], v170 offset:0
	ds_read_b128 v[158:161], v170 offset:0x1000
	ds_read_b128 v[162:165], v170 offset:0x2000
	ds_read_b128 v[166:169], v170 offset:0x3000
	s_waitcnt lgkmcnt(3)
	s_nop 0
	v_mfma_f32_16x16x32_bf16 v[170:173], v[154:157], v[146:149], 0
	v_mfma_f32_16x16x32_bf16 v[154:157], v[154:157], v[150:153], 0
	ds_read_b128 v[174:177], v225 offset:0
	s_waitcnt lgkmcnt(3)
	v_mfma_f32_16x16x32_bf16 v[202:205], v[158:161], v[146:149], 0
	v_mfma_f32_16x16x32_bf16 v[158:161], v[158:161], v[150:153], 0
	ds_read_b128 v[206:209], v225 offset:0x1000
	s_waitcnt lgkmcnt(3)
	v_mfma_f32_16x16x32_bf16 v[244:247], v[162:165], v[146:149], 0
	v_mfma_f32_16x16x32_bf16 v[162:165], v[162:165], v[150:153], 0
	ds_read_b128 v[248:251], v182 offset:0
	s_waitcnt lgkmcnt(3)
	v_mfma_f32_16x16x32_bf16 v[146:149], v[166:169], v[146:149], 0
	v_mfma_f32_16x16x32_bf16 v[150:153], v[166:169], v[150:153], 0
	ds_read_b128 v[166:169], v182 offset:0x1000
	ds_read_b128 v[232:235], v182 offset:0x2000
	ds_read_b128 v[236:239], v182 offset:0x3000
	s_waitcnt lgkmcnt(3)
	v_mfma_f32_16x16x32_bf16 v[170:173], v[248:251], v[174:177], v[170:173]
	v_mfma_f32_16x16x32_bf16 v[154:157], v[248:251], v[206:209], v[154:157]
	ds_read_b128 v[248:251], v227 offset:0
	s_waitcnt lgkmcnt(3)
	v_mfma_f32_16x16x32_bf16 v[202:205], v[166:169], v[174:177], v[202:205]
	v_mfma_f32_16x16x32_bf16 v[158:161], v[166:169], v[206:209], v[158:161]
	ds_read_b128 v[166:169], v227 offset:0x1000
	s_waitcnt lgkmcnt(3)
	v_mfma_f32_16x16x32_bf16 v[162:165], v[232:235], v[206:209], v[162:165]
	v_mfma_f32_16x16x32_bf16 v[244:247], v[232:235], v[174:177], v[244:247]
	ds_read_b128 v[232:235], v183 offset:0
	s_waitcnt lgkmcnt(3)
	v_mfma_f32_16x16x32_bf16 v[146:149], v[236:239], v[174:177], v[146:149]
	v_mfma_f32_16x16x32_bf16 v[150:153], v[236:239], v[206:209], v[150:153]
	ds_read_b128 v[174:177], v183 offset:0x1000
	ds_read_b128 v[206:209], v183 offset:0x2000
	ds_read_b128 v[236:239], v183 offset:0x3000
	s_waitcnt lgkmcnt(3)
	v_mfma_f32_16x16x32_bf16 v[170:173], v[232:235], v[248:251], v[170:173]
	v_mfma_f32_16x16x32_bf16 v[154:157], v[232:235], v[166:169], v[154:157]
	ds_read_b128 v[232:235], v229 offset:0
	s_waitcnt lgkmcnt(3)
	v_mfma_f32_16x16x32_bf16 v[202:205], v[174:177], v[248:251], v[202:205]
	v_mfma_f32_16x16x32_bf16 v[158:161], v[174:177], v[166:169], v[158:161]
	ds_read_b128 v[182:185], v229 offset:0x1000
	s_waitcnt lgkmcnt(3)
	v_mfma_f32_16x16x32_bf16 v[174:177], v[206:209], v[248:251], v[244:247]
	v_mfma_f32_16x16x32_bf16 v[206:209], v[206:209], v[166:169], v[162:165]
	ds_read_b128 v[244:247], v1 offset:0
	s_waitcnt lgkmcnt(3)
	v_mfma_f32_16x16x32_bf16 v[248:251], v[236:239], v[248:251], v[146:149]
	v_mfma_f32_16x16x32_bf16 v[236:239], v[236:239], v[166:169], v[150:153]
	ds_read_b128 v[150:153], v1 offset:0x1000
	ds_read_b128 v[240:243], v1 offset:0x2000
	ds_read_b128 v[210:213], v1 offset:0x3000
	s_waitcnt lgkmcnt(3)
	v_mfma_f32_16x16x32_bf16 v[162:165], v[244:247], v[232:235], v[170:173]
	v_mfma_f32_16x16x32_bf16 v[146:149], v[244:247], v[182:185], v[154:157]
	s_waitcnt lgkmcnt(2)
	v_mfma_f32_16x16x32_bf16 v[166:169], v[150:153], v[232:235], v[202:205]
	v_mfma_f32_16x16x32_bf16 v[150:153], v[150:153], v[182:185], v[158:161]
	s_waitcnt lgkmcnt(1)
	v_mfma_f32_16x16x32_bf16 v[170:173], v[240:243], v[232:235], v[174:177]
	v_mfma_f32_16x16x32_bf16 v[154:157], v[240:243], v[182:185], v[206:209]
	s_waitcnt lgkmcnt(0)
	v_mfma_f32_16x16x32_bf16 v[174:177], v[210:213], v[232:235], v[248:251]
	v_mfma_f32_16x16x32_bf16 v[158:161], v[210:213], v[182:185], v[236:239]
	s_nop 0
	s_nop 1
	v_max_f32_e32 v1, v162, v163
	v_max3_f32 v1, v1, v164, v165
	v_max3_f32 v1, v1, v166, v167
	v_max3_f32 v1, v1, v168, v169
	v_max3_f32 v1, v1, v170, v171
	v_max3_f32 v1, v1, v172, v173
	v_max3_f32 v1, v1, v174, v175
	v_max3_f32 v1, v1, v176, v177
	v_mov_b32_e32 v182, v1
	s_nop 1
	v_permlane16_swap_b32_e32 v1, v182
	v_max_f32_e32 v1, v1, v182
	v_mov_b32_e32 v182, v1
	s_nop 1
	v_permlane32_swap_b32_e32 v1, v182
	v_max_f32_e32 v203, v1, v182
	s_nop 1
	v_max_f32_e32 v1, v146, v147
	v_max3_f32 v1, v1, v148, v149
	v_max3_f32 v1, v1, v150, v151
	v_max3_f32 v1, v1, v152, v153
	v_max3_f32 v1, v1, v154, v155
	v_max3_f32 v1, v1, v156, v157
	v_max3_f32 v1, v1, v158, v159
	v_max3_f32 v1, v1, v160, v161
	v_mov_b32_e32 v182, v1
	s_nop 1
	v_permlane16_swap_b32_e32 v1, v182
	v_max_f32_e32 v1, v1, v182
	v_mov_b32_e32 v182, v1
	s_nop 1
	v_permlane32_swap_b32_e32 v1, v182
	v_max_f32_e32 v204, v1, v182
	v_sub_f32_e32 v1, v203, v231
	v_cmp_ge_f32_e32 vcc, s87, v1
	v_sub_f32_e32 v1, v204, v230
	v_cmp_ge_f32_e64 s[6:7], s87, v1
	s_and_b64 s[6:7], vcc, s[6:7]
	v_mov_b32_e32 v202, 1.0
	s_cmp_eq_u64 s[6:7], exec
	s_cbranch_scc0 .LBB0_712
	v_mov_b32_e32 v203, 1.0
.LBB0_706:
	v_min_f32_e32 v1, v202, v203
	v_cmp_gt_f32_e32 vcc, 1.0, v1
	s_cbranch_vccz .LBB0_710
	s_and_saveexec_b64 s[6:7], s[4:5]
	ds_write2_b32 v219, v202, v203 offset0:32 offset1:48
	s_or_b64 exec, exec, s[6:7]
	s_waitcnt lgkmcnt(0)
	ds_read_b128 v[182:185], v215 offset:128
	s_waitcnt lgkmcnt(0)
	v_pk_mul_f32 v[144:145], v[144:145], v[184:185]
	v_pk_mul_f32 v[142:143], v[142:143], v[182:183]
	v_pk_mul_f32 v[140:141], v[140:141], v[184:185]
	v_pk_mul_f32 v[138:139], v[138:139], v[182:183]
	v_pk_mul_f32 v[136:137], v[136:137], v[184:185]
	v_pk_mul_f32 v[134:135], v[134:135], v[182:183]
	v_pk_mul_f32 v[132:133], v[132:133], v[184:185]
	v_pk_mul_f32 v[130:131], v[130:131], v[182:183]
	v_pk_mul_f32 v[128:129], v[128:129], v[184:185]
	v_pk_mul_f32 v[126:127], v[126:127], v[182:183]
	v_pk_mul_f32 v[124:125], v[124:125], v[184:185]
	v_pk_mul_f32 v[122:123], v[122:123], v[182:183]
	v_pk_mul_f32 v[120:121], v[120:121], v[184:185]
	v_pk_mul_f32 v[118:119], v[118:119], v[182:183]
	v_pk_mul_f32 v[116:117], v[116:117], v[184:185]
	v_pk_mul_f32 v[114:115], v[114:115], v[182:183]
	v_pk_mul_f32 v[64:65], v[64:65], v[184:185]
	v_pk_mul_f32 v[62:63], v[62:63], v[182:183]
	v_pk_mul_f32 v[60:61], v[60:61], v[184:185]
	v_pk_mul_f32 v[58:59], v[58:59], v[182:183]
	v_pk_mul_f32 v[56:57], v[56:57], v[184:185]
	v_pk_mul_f32 v[54:55], v[54:55], v[182:183]
	v_pk_mul_f32 v[52:53], v[52:53], v[184:185]
	v_pk_mul_f32 v[50:51], v[50:51], v[182:183]
	v_pk_mul_f32 v[48:49], v[48:49], v[184:185]
	v_pk_mul_f32 v[46:47], v[46:47], v[182:183]
	v_pk_mul_f32 v[44:45], v[44:45], v[184:185]
	v_pk_mul_f32 v[42:43], v[42:43], v[182:183]
	v_pk_mul_f32 v[40:41], v[40:41], v[184:185]
	v_pk_mul_f32 v[38:39], v[38:39], v[182:183]
	v_pk_mul_f32 v[36:37], v[36:37], v[184:185]
	v_pk_mul_f32 v[34:35], v[34:35], v[182:183]
	ds_read_b128 v[182:185], v215 offset:192
	s_waitcnt lgkmcnt(0)
	v_pk_mul_f32 v[112:113], v[112:113], v[184:185]
	v_pk_mul_f32 v[110:111], v[110:111], v[182:183]
	v_pk_mul_f32 v[108:109], v[108:109], v[184:185]
	v_pk_mul_f32 v[106:107], v[106:107], v[182:183]
	v_pk_mul_f32 v[104:105], v[104:105], v[184:185]
	v_pk_mul_f32 v[102:103], v[102:103], v[182:183]
	v_pk_mul_f32 v[100:101], v[100:101], v[184:185]
	v_pk_mul_f32 v[98:99], v[98:99], v[182:183]
	v_pk_mul_f32 v[96:97], v[96:97], v[184:185]
	v_pk_mul_f32 v[94:95], v[94:95], v[182:183]
	v_pk_mul_f32 v[92:93], v[92:93], v[184:185]
	v_pk_mul_f32 v[90:91], v[90:91], v[182:183]
	v_pk_mul_f32 v[88:89], v[88:89], v[184:185]
	v_pk_mul_f32 v[86:87], v[86:87], v[182:183]
	v_pk_mul_f32 v[84:85], v[84:85], v[184:185]
	v_pk_mul_f32 v[82:83], v[82:83], v[182:183]
	v_pk_mul_f32 v[20:21], v[20:21], v[184:185]
	v_pk_mul_f32 v[18:19], v[18:19], v[182:183]
	v_pk_mul_f32 v[32:33], v[32:33], v[184:185]
	v_pk_mul_f32 v[30:31], v[30:31], v[182:183]
	v_pk_mul_f32 v[28:29], v[28:29], v[184:185]
	v_pk_mul_f32 v[26:27], v[26:27], v[182:183]
	v_pk_mul_f32 v[24:25], v[24:25], v[184:185]
	v_pk_mul_f32 v[22:23], v[22:23], v[182:183]
	v_pk_mul_f32 v[16:17], v[16:17], v[184:185]
	v_pk_mul_f32 v[14:15], v[14:15], v[182:183]
	v_pk_mul_f32 v[12:13], v[12:13], v[184:185]
	v_pk_mul_f32 v[10:11], v[10:11], v[182:183]
	v_pk_mul_f32 v[8:9], v[8:9], v[184:185]
	v_pk_mul_f32 v[6:7], v[6:7], v[182:183]
	v_pk_mul_f32 v[4:5], v[4:5], v[184:185]
	v_pk_mul_f32 v[2:3], v[2:3], v[182:183]

; __device__ __forceinline__ void partialSM16(f32x4 (&s)[4][2], float (&m_reg)[2], float (&alpha)[2], const float C, const float thr_s) {
;     ...
;   else {
; #pragma unroll
;     for (int qt = 0; qt < 2; ++qt) { mn[qt] = fmaxf(m_reg[qt], pmax[qt]); alpha[qt] = __builtin_amdgcn_exp2f((m_reg[qt] - mn[qt]) * C); m_reg[qt] = mn[qt]; } }
.LBB0_712:
	s_nop 1
	v_max_f32_e32 v1, v231, v203
	v_sub_f32_e32 v182, v231, v1
	v_mul_f32_e32 v182, 0x3e0293ee, v182
	v_exp_f32_e32 v202, v182
	s_nop 1
	v_max_f32_e32 v182, v230, v204
	v_sub_f32_e32 v183, v230, v182
	v_mul_f32_e32 v183, 0x3e0293ee, v183
	v_exp_f32_e32 v203, v183
	v_mov_b32_e32 v231, v1
	v_mov_b32_e32 v230, v182
	s_branch .LBB0_706

; __device__ __forceinline__ unsigned pk2(float lo, float hi) { const f32x2_g v = {lo, hi}; return __builtin_bit_cast(unsigned, __builtin_convertvector(v, bf16x2_g)); }
; __device__ __forceinline__ float shflx(float v, int mask, int lane) { return __int_as_float(__builtin_amdgcn_ds_bpermute((lane ^ mask) << 2, __float_as_int(v))); }
; #define REP(ph) for (int _rep = 0; _rep < (((PROBE_DUP >> (ph)) & 1) ? 2 : 1); ++_rep)
; __global__ void __launch_bounds__(512, 2) mk_fwd(Args args) {
;     ...
;             REP(PH_DIFFC) for (int t = gw; t < T; t += NGW) {
;                 const int h = lane >> 4, c0 = (lane & 15) * 4;
;                 const bf16_t* o1 = OD + (size_t)t * 1024 + h * 256; const bf16_t* o2 = o1 + (size_t)T * 1024;
;                 f32x4 d[4], e2[4]; float ss = 0.f;
; #pragma unroll
;                 for (int i = 0; i < 4; ++i) { const u32x2 w1 = __builtin_nontemporal_load((const u32x2*)(o1 + c0 + 64 * i)), w2 = __builtin_nontemporal_load((const u32x2*)(o2 + c0 + 64 * i));
;                     d[i] = (f32x4){__uint_as_float(w1.x << 16), __uint_as_float(w1.x & 0xffff0000u), __uint_as_float(w1.y << 16), __uint_as_float(w1.y & 0xffff0000u)};
;                     e2[i] = (f32x4){__uint_as_float(w2.x << 16), __uint_as_float(w2.x & 0xffff0000u), __uint_as_float(w2.y << 16), __uint_as_float(w2.y & 0xffff0000u)}; }
;                 __builtin_amdgcn_sched_barrier(0);
; #pragma unroll
;                 for (int i = 0; i < 4; ++i) { d[i] = d[i] - e2[i] * lam; ss += d[i][0] * d[i][0] + d[i][1] * d[i][1] + d[i][2] * d[i][2] + d[i][3] * d[i][3]; }
;                 ss += shflx(ss, 1, lane); ss += shflx(ss, 2, lane); ss += shflx(ss, 4, lane); ss += shflx(ss, 8, lane);
;                 const float rstd = rsqrtf(ss * (1.0f / 256.0f) + EPS);
; #pragma unroll
;                 for (int i = 0; i < 4; ++i) { const f32x4 y = d[i] * rstd * gsub[i];
;                     u32x2 w; w.x = pk2(y[0], y[1]); w.y = pk2(y[2], y[3]); *(u32x2*)(YD + (size_t)t * 1024 + h * 256 + c0 + 64 * i) = w; }
;             }
.LBB0_775:
	v_add_co_u32_e32 v38, vcc, 0xfde00000, v20
	s_nop 1
	v_addc_co_u32_e32 v39, vcc, -1, v21, vcc
	global_load_dwordx2 v[22:23], v[38:39], off offset:-384 nt
	global_load_dwordx2 v[26:27], v[20:21], off offset:-384 nt
	s_waitcnt vmcnt(1)
	v_lshlrev_b32_e32 v24, 16, v22
	v_and_b32_e32 v25, 0xffff0000, v22
	v_lshlrev_b32_e32 v30, 16, v23
	v_and_b32_e32 v31, 0xffff0000, v23
	s_waitcnt vmcnt(0)
	v_lshlrev_b32_e32 v28, 16, v26
	v_and_b32_e32 v29, 0xffff0000, v26
	v_lshlrev_b32_e32 v32, 16, v27
	v_and_b32_e32 v33, 0xffff0000, v27
	global_load_dwordx2 v[22:23], v[38:39], off offset:-256 nt
	global_load_dwordx2 v[26:27], v[20:21], off offset:-256 nt
	s_waitcnt vmcnt(1)
	v_lshlrev_b32_e32 v34, 16, v22
	s_waitcnt vmcnt(0)
	v_lshlrev_b32_e32 v36, 16, v26
	v_and_b32_e32 v37, 0xffff0000, v26
	v_lshlrev_b32_e32 v42, 16, v27
	v_and_b32_e32 v43, 0xffff0000, v27
	global_load_dwordx2 v[26:27], v[38:39], off offset:-128 nt
	global_load_dwordx2 v[44:45], v[20:21], off offset:-128 nt
	v_and_b32_e32 v35, 0xffff0000, v22
	v_lshlrev_b32_e32 v40, 16, v23
	v_and_b32_e32 v41, 0xffff0000, v23
	s_waitcnt vmcnt(1)
	v_lshlrev_b32_e32 v22, 16, v26
	v_and_b32_e32 v23, 0xffff0000, v26
	v_lshlrev_b32_e32 v46, 16, v27
	v_and_b32_e32 v47, 0xffff0000, v27
	s_waitcnt vmcnt(0)
	v_lshlrev_b32_e32 v26, 16, v44
	v_and_b32_e32 v27, 0xffff0000, v44
	v_lshlrev_b32_e32 v48, 16, v45
	v_and_b32_e32 v49, 0xffff0000, v45
	global_load_dwordx2 v[44:45], v[38:39], off nt
	global_load_dwordx2 v[54:55], v[20:21], off nt
	s_waitcnt vmcnt(1)
	v_lshlrev_b32_e32 v38, 16, v44
	v_and_b32_e32 v39, 0xffff0000, v44
	v_lshlrev_b32_e32 v44, 16, v45
	v_and_b32_e32 v45, 0xffff0000, v45
	s_waitcnt vmcnt(0)
	v_lshlrev_b32_e32 v56, 16, v54
	v_and_b32_e32 v57, 0xffff0000, v54
	v_lshlrev_b32_e32 v54, 16, v55
	v_and_b32_e32 v55, 0xffff0000, v55
	v_xor_b32_e32 v58, 0x80000000, v2
	v_mov_b32_e32 v59, v58
	v_pk_fma_f32 v[30:31], v[58:59], v[32:33], v[30:31]
	v_pk_fma_f32 v[24:25], v[2:3], v[28:29], v[24:25] neg_lo:[1,0,0] neg_hi:[1,0,0]
	v_pk_fma_f32 v[32:33], v[2:3], v[36:37], v[34:35] neg_lo:[1,0,0] neg_hi:[1,0,0]
	v_mov_b32_e32 v36, v25
	v_mov_b32_e32 v37, v33
	v_pk_fma_f32 v[28:29], v[58:59], v[42:43], v[40:41]
	v_mov_b32_e32 v34, v24
	v_mov_b32_e32 v35, v32
	v_pk_mul_f32 v[36:37], v[36:37], v[36:37]
	v_pk_fma_f32 v[22:23], v[2:3], v[26:27], v[22:23] neg_lo:[1,0,0] neg_hi:[1,0,0]
	v_pk_fma_f32 v[34:35], v[34:35], v[34:35], v[36:37]
	v_mov_b32_e32 v36, v30
	v_mov_b32_e32 v37, v28
	v_pk_fma_f32 v[38:39], v[2:3], v[56:57], v[38:39] neg_lo:[1,0,0] neg_hi:[1,0,0]
	v_pk_fma_f32 v[34:35], v[36:37], v[36:37], v[34:35]
	v_mov_b32_e32 v36, v31
	v_mov_b32_e32 v37, v29
	v_mov_b32_e32 v42, v23
	v_mov_b32_e32 v43, v39
	v_pk_fma_f32 v[34:35], v[36:37], v[36:37], v[34:35]
	v_pk_fma_f32 v[36:37], v[58:59], v[48:49], v[46:47]
	v_pk_fma_f32 v[26:27], v[58:59], v[54:55], v[44:45]
	v_mov_b32_e32 v40, v22
	v_mov_b32_e32 v41, v38
	v_pk_mul_f32 v[42:43], v[42:43], v[42:43]
	v_add_f32_e32 v1, v34, v35
	v_pk_fma_f32 v[40:41], v[40:41], v[40:41], v[42:43]
	v_mov_b32_e32 v42, v36
	v_mov_b32_e32 v43, v26
	v_pk_fma_f32 v[40:41], v[42:43], v[42:43], v[40:41]
	v_mov_b32_e32 v42, v37
	v_mov_b32_e32 v43, v27
	v_pk_fma_f32 v[40:41], v[42:43], v[42:43], v[40:41]
	s_mov_b32 s0, 0xfbc00000
	v_add_f32_e32 v1, v1, v40
	v_add_f32_e32 v1, v1, v41
	s_add_i32 s4, s4, s34
	s_cmpk_gt_i32 s4, 0x43ff
	s_waitcnt lgkmcnt(0)
	s_nop 1
	v_add_f32_dpp v1, v1, v1 quad_perm:[1,0,3,2] row_mask:0xf bank_mask:0xf
	s_waitcnt lgkmcnt(0)
	s_nop 1
	v_add_f32_dpp v1, v1, v1 quad_perm:[2,3,0,1] row_mask:0xf bank_mask:0xf
	s_waitcnt lgkmcnt(0)
	s_nop 1
	v_add_f32_dpp v1, v1, v1 row_half_mirror row_mask:0xf bank_mask:0xf
	s_waitcnt lgkmcnt(0)
	s_nop 1
	v_add_f32_dpp v1, v1, v1 row_mirror row_mask:0xf bank_mask:0xf
	v_fmamk_f32 v1, v1, 0x3b800000, v230
	v_cmp_gt_f32_e32 vcc, s85, v1
	v_mul_f32_e32 v34, 0x4b800000, v1
	s_nop 0
	v_cndmask_b32_e32 v1, v1, v34, vcc
	v_rsq_f32_e32 v1, v1
	s_nop 0
	v_mul_f32_e32 v34, 0x45800000, v1
	v_cndmask_b32_e32 v34, v1, v34, vcc
	v_pk_mul_f32 v[24:25], v[34:35], v[24:25] op_sel_hi:[0,1]
	v_pk_mul_f32 v[30:31], v[34:35], v[30:31] op_sel_hi:[0,1]
	v_pk_mul_f32 v[30:31], v[30:31], v[4:5]
	v_pk_mul_f32 v[24:25], v[24:25], v[6:7]
	v_pk_mul_f32 v[28:29], v[34:35], v[28:29] op_sel_hi:[0,1]
	v_cvt_pk_bf16_f32 v24, v24, v25
	v_cvt_pk_bf16_f32 v25, v30, v31
	v_add_co_u32_e32 v30, vcc, s0, v20
	v_pk_mul_f32 v[28:29], v[28:29], v[8:9]
	s_nop 0
	v_addc_co_u32_e32 v31, vcc, -1, v21, vcc
	global_store_dwordx2 v[30:31], v[24:25], off offset:-384
	v_pk_mul_f32 v[24:25], v[34:35], v[32:33] op_sel_hi:[0,1]
	v_pk_mul_f32 v[24:25], v[24:25], v[10:11]
	v_pk_mul_f32 v[22:23], v[34:35], v[22:23] op_sel_hi:[0,1]
	v_cvt_pk_bf16_f32 v24, v24, v25
	v_cvt_pk_bf16_f32 v25, v28, v29
	global_store_dwordx2 v[30:31], v[24:25], off offset:-256
	v_pk_mul_f32 v[24:25], v[34:35], v[36:37] op_sel_hi:[0,1]
	v_pk_mul_f32 v[24:25], v[24:25], v[12:13]
	v_pk_mul_f32 v[22:23], v[22:23], v[14:15]
	v_lshl_add_u64 v[20:21], v[20:21], 0, s[12:13]
	v_cvt_pk_bf16_f32 v22, v22, v23
	v_cvt_pk_bf16_f32 v23, v24, v25
	global_store_dwordx2 v[30:31], v[22:23], off offset:-128
	v_pk_mul_f32 v[22:23], v[34:35], v[38:39] op_sel_hi:[0,1]
	v_pk_mul_f32 v[24:25], v[34:35], v[26:27] op_sel_hi:[0,1]
	v_pk_mul_f32 v[24:25], v[24:25], v[16:17]
	v_pk_mul_f32 v[22:23], v[22:23], v[18:19]
	s_nop 0
	v_cvt_pk_bf16_f32 v22, v22, v23
	v_cvt_pk_bf16_f32 v23, v24, v25
	global_store_dwordx2 v[30:31], v[22:23], off
	s_cbranch_scc0 .LBB0_775
